# attention unit tail: the 32 V reads of the final P.V get their own VGPRs, first 14 issued under the softmax finish, rest in a rolling window, counted lgkmcnt
# baseline (speedup 1.0000x reference)
.LBB0_985:
	v_exp_f32_e32 v102, v44
	v_add_f32_e32 v44, 0, v92
	v_add_f32_e32 v44, v93, v44
	v_add_f32_e32 v44, v94, v44
	v_add_f32_e32 v44, v95, v44
	v_exp_f32_e32 v36, v36
	v_add_f32_e32 v44, v44, v96
	v_exp_f32_e32 v37, v37
	v_add_f32_e32 v44, v97, v44
	v_exp_f32_e32 v38, v38
	v_add_f32_e32 v44, v98, v44
	v_exp_f32_e32 v39, v39
	v_add_f32_e32 v44, v99, v44
	v_exp_f32_e32 v40, v40
	v_add_f32_e32 v44, v36, v44
	v_exp_f32_e32 v41, v41
	v_add_f32_e32 v44, v37, v44
	v_exp_f32_e32 v42, v42
	v_add_f32_e32 v44, v38, v44
	v_exp_f32_e32 v43, v43
	v_add_f32_e32 v44, v39, v44
	v_add_f32_e32 v44, v40, v44
	v_add_f32_e32 v44, v41, v44
	v_add_f32_e32 v44, v42, v44
	v_pk_mul_f32 v[60:61], v[200:201], v[192:193]
	s_waitcnt vmcnt(0)
	v_add_f32_e32 v100, v43, v44
	v_add_f32_e32 v60, v60, v144
	s_barrier
	ds_read_b64_tr_b16 v[124:125], v219
	ds_read_b64_tr_b16 v[126:127], v219 offset:4096
	ds_read_b64_tr_b16 v[128:129], v219 offset:8192
	ds_read_b64_tr_b16 v[130:131], v219 offset:12288
	ds_read_b64_tr_b16 v[132:133], v196
	ds_read_b64_tr_b16 v[134:135], v196 offset:4096
	ds_read_b64_tr_b16 v[136:137], v196 offset:8192
	ds_read_b64_tr_b16 v[138:139], v196 offset:12288
	ds_read_b64_tr_b16 v[140:141], v219 offset:512
	ds_read_b64_tr_b16 v[142:143], v219 offset:4608
	ds_read_b64_tr_b16 v[148:149], v219 offset:8704
	ds_read_b64_tr_b16 v[150:151], v219 offset:12800
	ds_read_b64_tr_b16 v[152:153], v196 offset:512
	ds_read_b64_tr_b16 v[154:155], v196 offset:4608
	v_add_f32_e32 v101, v61, v145
	v_fmac_f32_e32 v100, v60, v114
	v_cvt_pk_bf16_f32 v60, v92, v93
	v_cvt_pk_bf16_f32 v61, v94, v95
	v_cvt_pk_bf16_f32 v62, v96, v97
	v_cvt_pk_bf16_f32 v63, v98, v99
	v_cvt_pk_bf16_f32 v36, v36, v37
	v_cvt_pk_bf16_f32 v37, v38, v39
	v_cvt_pk_bf16_f32 v38, v40, v41
	v_add_f32_e32 v40, 0, v88
	v_add_f32_e32 v40, v89, v40
	v_add_f32_e32 v40, v90, v40
	v_add_f32_e32 v40, v91, v40
	v_exp_f32_e32 v48, v48
	v_add_f32_e32 v40, v40, v56
	v_exp_f32_e32 v49, v49
	v_add_f32_e32 v40, v57, v40
	v_exp_f32_e32 v50, v50
	v_add_f32_e32 v40, v58, v40
	v_exp_f32_e32 v51, v51
	v_add_f32_e32 v40, v59, v40
	v_add_f32_e32 v40, v48, v40
	s_lshl_b32 s2, s24, 12
	v_exp_f32_e32 v103, v45
	v_add_f32_e32 v40, v49, v40
	s_add_u32 s2, s26, s2
	v_exp_f32_e32 v104, v46
	v_add_f32_e32 v40, v50, v40
	s_addc_u32 s6, s27, 0
	s_lshl_b32 s4, s44, 7
	v_exp_f32_e32 v47, v47
	v_add_f32_e32 v40, v51, v40
	s_ashr_i32 s5, s4, 31
	v_add_f32_e32 v40, v102, v40
	s_lshl_b64 s[4:5], s[4:5], 1
	v_add_f32_e32 v40, v103, v40
	s_add_u32 s2, s2, s4
	v_add_f32_e32 v40, v104, v40
	s_addc_u32 s4, s6, s5
	v_add_f32_e32 v92, v47, v40
	s_add_u32 s6, s2, 0x3c800000
	v_cvt_pk_bf16_f32 v39, v42, v43
	s_addc_u32 s7, s4, 0
	v_fmac_f32_e32 v92, v101, v112
	v_cvt_pk_bf16_f32 v88, v88, v89
	v_cvt_pk_bf16_f32 v89, v90, v91
	v_cvt_pk_bf16_f32 v90, v56, v57
	v_cvt_pk_bf16_f32 v91, v58, v59
	v_cvt_pk_bf16_f32 v44, v48, v49
	v_cvt_pk_bf16_f32 v45, v50, v51
	v_cvt_pk_bf16_f32 v46, v102, v103
	v_cvt_pk_bf16_f32 v47, v104, v47
	s_waitcnt lgkmcnt(12)
	v_mfma_f32_16x16x32_bf16 v[12:15], v[124:127], v[60:63], v[12:15]
	v_mfma_f32_16x16x32_bf16 v[20:23], v[124:127], v[88:91], v[20:23]
	ds_read_b64_tr_b16 v[156:157], v196 offset:8704
	ds_read_b64_tr_b16 v[158:159], v196 offset:12800
	s_waitcnt lgkmcnt(12)
	v_mfma_f32_16x16x32_bf16 v[40:43], v[128:131], v[36:39], v[12:15]
	s_nop 5
	s_waitcnt lgkmcnt(10)
	v_mfma_f32_16x16x32_bf16 v[24:27], v[132:135], v[60:63], v[24:27]
	v_mfma_f32_16x16x32_bf16 v[12:15], v[132:135], v[88:91], v[28:31]
	ds_read_b64_tr_b16 v[164:165], v219 offset:9216
	ds_read_b64_tr_b16 v[166:167], v219 offset:13312
	s_nop 2
	s_waitcnt lgkmcnt(10)
	v_mfma_f32_16x16x32_bf16 v[24:27], v[136:139], v[36:39], v[24:27]
	v_mfma_f32_16x16x32_bf16 v[12:15], v[136:139], v[44:47], v[12:15]
	ds_read_b64_tr_b16 v[168:169], v196 offset:1024
	ds_read_b64_tr_b16 v[170:171], v196 offset:5120
	s_waitcnt lgkmcnt(10)
	v_mfma_f32_16x16x32_bf16 v[0:3], v[140:143], v[60:63], v[0:3]
	v_mfma_f32_16x16x32_bf16 v[4:7], v[140:143], v[88:91], v[4:7]
	ds_read_b64_tr_b16 v[172:173], v196 offset:9216
	ds_read_b64_tr_b16 v[174:175], v196 offset:13312
	v_mfma_f32_16x16x32_bf16 v[20:23], v[128:131], v[44:47], v[20:23]
	ds_read_b64_tr_b16 v[160:161], v219 offset:1024
	ds_read_b64_tr_b16 v[162:163], v219 offset:5120
	s_waitcnt lgkmcnt(12)
	v_mfma_f32_16x16x32_bf16 v[48:51], v[148:151], v[36:39], v[0:3]
	s_nop 2
	s_waitcnt lgkmcnt(10)
	v_mfma_f32_16x16x32_bf16 v[8:11], v[152:155], v[60:63], v[8:11]
	v_mfma_f32_16x16x32_bf16 v[0:3], v[152:155], v[88:91], v[16:19]
	ds_read_b64_tr_b16 v[184:185], v219 offset:9728
	ds_read_b64_tr_b16 v[186:187], v219 offset:13824
	s_nop 2
	v_mfma_f32_16x16x32_bf16 v[4:7], v[148:151], v[44:47], v[4:7]
	ds_read_b64_tr_b16 v[176:177], v219 offset:1536
	ds_read_b64_tr_b16 v[178:179], v219 offset:5632
	s_waitcnt lgkmcnt(12)
	v_mfma_f32_16x16x32_bf16 v[28:31], v[156:159], v[36:39], v[8:11]
	s_nop 2
	v_mfma_f32_16x16x32_bf16 v[0:3], v[156:159], v[44:47], v[0:3]
	ds_read_b64_tr_b16 v[188:189], v196 offset:1536
	ds_read_b64_tr_b16 v[190:191], v196 offset:5632
	s_waitcnt lgkmcnt(6)
	v_mfma_f32_16x16x32_bf16 v[16:19], v[160:163], v[60:63], v[80:83]
	v_mfma_f32_16x16x32_bf16 v[8:11], v[160:163], v[88:91], v[84:87]
	ds_read_b64_tr_b16 v[192:193], v196 offset:9728
	ds_read_b64_tr_b16 v[194:195], v196 offset:13824
	v_mfma_f32_16x16x32_bf16 v[80:83], v[164:167], v[36:39], v[16:19]
	v_mfma_f32_16x16x32_bf16 v[16:19], v[164:167], v[44:47], v[8:11]
	s_nop 5
	v_mfma_f32_16x16x32_bf16 v[56:59], v[168:171], v[60:63], v[72:75]
	s_nop 2
	v_mfma_f32_16x16x32_bf16 v[8:11], v[168:171], v[88:91], v[76:79]
	v_mfma_f32_16x16x32_bf16 v[56:59], v[172:175], v[36:39], v[56:59]
	v_mfma_f32_16x16x32_bf16 v[8:11], v[172:175], v[44:47], v[8:11]
	s_waitcnt lgkmcnt(4)
	v_mfma_f32_16x16x32_bf16 v[64:67], v[176:179], v[60:63], v[64:67]
	v_mfma_f32_16x16x32_bf16 v[68:71], v[176:179], v[88:91], v[68:71]
	v_mfma_f32_16x16x32_bf16 v[76:79], v[184:187], v[36:39], v[64:67]
	v_mfma_f32_16x16x32_bf16 v[64:67], v[184:187], v[44:47], v[68:71]
	s_nop 2
	s_waitcnt lgkmcnt(2)
	v_mfma_f32_16x16x32_bf16 v[32:35], v[188:191], v[60:63], v[32:35]
	v_mfma_f32_16x16x32_bf16 v[52:55], v[188:191], v[88:91], v[52:55]
	s_waitcnt lgkmcnt(0)
	v_mfma_f32_16x16x32_bf16 v[32:35], v[192:195], v[36:39], v[32:35]
	v_mfma_f32_16x16x32_bf16 v[36:39], v[192:195], v[44:47], v[52:55]
	s_setprio 0
	v_mbcnt_lo_u32_b32 v44, -1, 0
	v_mbcnt_hi_u32_b32 v44, -1, v44
	v_readlane_b32 s2, v254, 39
	v_lshlrev_b32_e32 v45, 2, v44
	v_xor_b32_e32 v46, 64, v45
	ds_bpermute_b32 v47, v46, v100
	v_xor_b32_e32 v45, 0x80, v45
	v_ashrrev_i32_e32 v53, 1, v44
	v_lshlrev_b32_e32 v44, 12, v44
	v_and_b32_e32 v44, 0xf000, v44
	s_waitcnt lgkmcnt(0)
	v_add_f32_e32 v47, v100, v47
	ds_bpermute_b32 v52, v45, v47
	v_and_b32_e32 v53, -8, v53
	v_or_b32_e32 v44, s2, v44
	v_add_u32_e32 v44, v44, v53
	s_add_i32 s83, s83, 1
	s_waitcnt lgkmcnt(0)
	v_add_f32_e32 v47, v47, v52
	v_rcp_f32_e32 v47, v47
	s_mov_b32 s2, 0
	v_mul_f32_e32 v40, v40, v47
	v_mul_f32_e32 v41, v41, v47
	v_mul_f32_e32 v24, v24, v47
	v_mul_f32_e32 v25, v25, v47
	v_mul_f32_e32 v42, v42, v47
	v_mul_f32_e32 v43, v43, v47
	v_cvt_pk_bf16_f32 v40, v40, v41
	v_cvt_pk_bf16_f32 v41, v42, v43
	global_store_dwordx2 v44, v[40:41], s[6:7]
	v_cvt_pk_bf16_f32 v24, v24, v25
	v_mul_f32_e32 v25, v26, v47
	v_mul_f32_e32 v26, v27, v47
	v_cvt_pk_bf16_f32 v25, v25, v26
	global_store_dwordx2 v44, v[24:25], s[6:7] offset:32
	v_mul_f32_e32 v24, v48, v47
	v_mul_f32_e32 v25, v49, v47
	v_cvt_pk_bf16_f32 v24, v24, v25
	v_mul_f32_e32 v25, v50, v47
	v_mul_f32_e32 v26, v51, v47
	v_cvt_pk_bf16_f32 v25, v25, v26
	global_store_dwordx2 v44, v[24:25], s[6:7] offset:64
	v_mul_f32_e32 v24, v28, v47
	v_mul_f32_e32 v25, v29, v47
	v_cvt_pk_bf16_f32 v24, v24, v25
	v_mul_f32_e32 v25, v30, v47
	v_mul_f32_e32 v26, v31, v47
	v_cvt_pk_bf16_f32 v25, v25, v26
	global_store_dwordx2 v44, v[24:25], s[6:7] offset:96
	v_mul_f32_e32 v24, v80, v47
	v_mul_f32_e32 v25, v81, v47
	v_cvt_pk_bf16_f32 v24, v24, v25
	v_mul_f32_e32 v25, v82, v47
	v_mul_f32_e32 v26, v83, v47
	v_cvt_pk_bf16_f32 v25, v25, v26
	global_store_dwordx2 v44, v[24:25], s[6:7] offset:128
	v_mul_f32_e32 v24, v56, v47
	v_mul_f32_e32 v25, v57, v47
	v_cvt_pk_bf16_f32 v24, v24, v25
	v_mul_f32_e32 v25, v58, v47
	v_mul_f32_e32 v26, v59, v47
	v_cvt_pk_bf16_f32 v25, v25, v26
	ds_bpermute_b32 v26, v46, v92
	global_store_dwordx2 v44, v[24:25], s[6:7] offset:160
	v_mul_f32_e32 v24, v76, v47
	v_mul_f32_e32 v25, v77, v47
	v_cvt_pk_bf16_f32 v24, v24, v25
	v_mul_f32_e32 v25, v78, v47
	v_mul_f32_e32 v27, v79, v47
	v_cvt_pk_bf16_f32 v25, v25, v27
	global_store_dwordx2 v44, v[24:25], s[6:7] offset:192
	s_waitcnt lgkmcnt(0)
	v_add_f32_e32 v25, v92, v26
	ds_bpermute_b32 v26, v45, v25
	v_mul_f32_e32 v24, v32, v47
	v_mul_f32_e32 v27, v33, v47
	v_cvt_pk_bf16_f32 v24, v24, v27
	v_mul_f32_e32 v27, v34, v47
	s_waitcnt lgkmcnt(0)
	v_add_f32_e32 v25, v25, v26
	v_rcp_f32_e32 v26, v25
	v_mul_f32_e32 v28, v35, v47
	v_cvt_pk_bf16_f32 v25, v27, v28
	global_store_dwordx2 v44, v[24:25], s[6:7] offset:224
	v_mul_f32_e32 v20, v20, v26
	v_mul_f32_e32 v21, v21, v26
	v_add_u32_e32 v24, 0x10000, v44
	v_cvt_pk_bf16_f32 v20, v20, v21
	v_mul_f32_e32 v21, v22, v26
	v_mul_f32_e32 v12, v12, v26
	v_mul_f32_e32 v13, v13, v26
	v_mul_f32_e32 v22, v23, v26
	v_cvt_pk_bf16_f32 v21, v21, v22
	global_store_dwordx2 v24, v[20:21], s[6:7]
	v_cvt_pk_bf16_f32 v12, v12, v13
	v_mul_f32_e32 v13, v14, v26
	v_mul_f32_e32 v4, v4, v26
	v_mul_f32_e32 v5, v5, v26
	v_mul_f32_e32 v14, v15, v26
	v_cvt_pk_bf16_f32 v13, v13, v14
	global_store_dwordx2 v24, v[12:13], s[6:7] offset:32
	v_cvt_pk_bf16_f32 v4, v4, v5
	v_mul_f32_e32 v5, v6, v26
	v_mul_f32_e32 v0, v0, v26
	v_mul_f32_e32 v1, v1, v26
	v_mul_f32_e32 v6, v7, v26
	v_cvt_pk_bf16_f32 v5, v5, v6
	global_store_dwordx2 v24, v[4:5], s[6:7] offset:64
	v_cvt_pk_bf16_f32 v0, v0, v1
	v_mul_f32_e32 v1, v2, v26
	v_mul_f32_e32 v2, v3, v26
	v_cvt_pk_bf16_f32 v1, v1, v2
	global_store_dwordx2 v24, v[0:1], s[6:7] offset:96
	v_mul_f32_e32 v0, v16, v26
	v_mul_f32_e32 v1, v17, v26
	v_cvt_pk_bf16_f32 v0, v0, v1
	v_mul_f32_e32 v1, v18, v26
	v_mul_f32_e32 v2, v19, v26
	v_cvt_pk_bf16_f32 v1, v1, v2
	global_store_dwordx2 v24, v[0:1], s[6:7] offset:128
	v_mul_f32_e32 v0, v8, v26
	v_mul_f32_e32 v1, v9, v26
	v_cvt_pk_bf16_f32 v0, v0, v1
	v_mul_f32_e32 v1, v10, v26
	v_mul_f32_e32 v2, v11, v26
	v_cvt_pk_bf16_f32 v1, v1, v2
	global_store_dwordx2 v24, v[0:1], s[6:7] offset:160
	v_mul_f32_e32 v0, v64, v26
	v_mul_f32_e32 v1, v65, v26
	v_cvt_pk_bf16_f32 v0, v0, v1
	v_mul_f32_e32 v1, v66, v26
	v_mul_f32_e32 v2, v67, v26
	v_cvt_pk_bf16_f32 v1, v1, v2
	global_store_dwordx2 v24, v[0:1], s[6:7] offset:192
	v_mul_f32_e32 v0, v36, v26
	v_mul_f32_e32 v1, v37, v26
	v_cvt_pk_bf16_f32 v0, v0, v1
	v_mul_f32_e32 v1, v38, v26
	v_mul_f32_e32 v2, v39, v26
	v_cvt_pk_bf16_f32 v1, v1, v2
	global_store_dwordx2 v24, v[0:1], s[6:7] offset:224
	s_waitcnt lgkmcnt(0)
	s_barrier
	s_cmpk_gt_i32 s2, 0x4e
	s_cbranch_scc1 .LBB0_840
	s_branch .LBB0_943
